# attention A loop: one static s_setprio 1 for waves 4-7 (reset at loop exit)
# speedup vs baseline: 1.0041x; 1.0041x over previous
; __device__ __forceinline__ int v_rd_base(int lane) { return ((lane & 3) << 3) | (((lane >> 2) & 3) << 6) | (((lane >> 4) & 1) << 5) | (((lane >> 5) & 1) << 8); }
; __device__ __forceinline__ void unit(const bf16* Qb, const bf16* __restrict__ Kh, const bf16* __restrict__ Vh, bf16* Ob, float lam, float post, const float* __restrict__ gsub, char* lds) {
;   int tid_ = threadIdx.x; asm volatile("" : "+v"(tid_));
;   const int tid = tid_, wid = __builtin_amdgcn_readfirstlane(tid >> 6), lane = tid & 63, r32 = lane & 31, hi = lane >> 5;
;   const int mp = wid >> 2, wq = wid & 3;
;   typedef __attribute__((address_space(3))) unsigned lds_u32;
;   float* ws = (float*)(lds + WS_OFF) + wid * 64; float* li_l = ws; float* al_l = ws + 32;
;   float m_reg = 0.f, l_reg = 0; f32x16 o[4] = {}; bf16x8 qr[4]; f32x16 negm = f32x16{};
;   const bf16* Qw = Qb + (long)(wq * QBLK + r32) * LD + mp * 64 + hi * 8;
; #pragma unroll
;   for (int d0 = 0; d0 < 4; ++d0) qr[d0] = ld8(Qw + d0 * 16);
;   const int vb0 = (int)(uintptr_t)lds + v_rd_base(lane);
;   unsigned kof[2], vof[2];
; #pragma unroll
;   for (int n = 0; n < 2; ++n) { const int c = 2 * wid + n;
;     { const int row = 4 * c + (lane >> 4), lc = (lane & 15) ^ (row & 15); kof[n] = (unsigned)(row * LD + 8 * lc) * 2u; }
;     { const int st = 2 * c + (lane >> 5), p = lane & 31, k = 8 * (st >> 2) + (p >> 2), col = 32 * (st & 3) + 8 * (p & 3); vof[n] = (unsigned)(k * LD + col) * 2u; } }
;     ...
;   f32x16 pA0, pA1, pB0, pB1; float alA, alB; bf16x8 pa0, pa1, pa2, pa3; constexpr int NT = 4096 / KVBLK;
;   DMA_TILE(0, 0); DMA_TILE(1, 32768); DMA_TILE(2, 65536);
;   asm volatile("s_waitcnt vmcnt(0)" ::: "memory"); __syncthreads();
;   qkt(pA0, pA1, (const bf16*)(lds + 16384), qr, r32, hi, mp, negm); partialSM<true>(pA0, pA1, m_reg, negm, alA);
.LBB0_196:
	s_lshl_b32 s8, s24, 1
	s_and_b32 s10, s8, 0x300
	s_ashr_i32 s8, s0, 7
	s_ashr_i32 s9, s8, 31
	s_lshl_b32 s11, s0, 17
	s_and_b32 s11, s11, 0x3e0000
	s_lshl_b64 vcc, s[8:9], 22
	s_add_u32 s8, s42, vcc_lo
	s_addc_u32 s9, s43, vcc_hi
	s_add_u32 s8, s8, s11
	s_addc_u32 s9, s9, 0
	s_lshl_b32 s11, s0, 3
	s_and_b32 s11, s11, 0x300
	s_add_u32 s22, s8, s11
	s_addc_u32 s23, s9, 0
	s_add_u32 s8, s29, vcc_lo
	s_addc_u32 s9, s20, vcc_hi
	s_add_u32 s40, s8, s11
	s_addc_u32 s41, s9, 0
	s_add_u32 s8, s3, vcc_lo
	s_addc_u32 s9, s1, vcc_hi
	s_add_u32 s48, s8, s11
	v_mov_b32_e32 v165, v218
	s_addc_u32 s49, s9, 0
	v_mov_b32_e32 v167, v189
	v_readfirstlane_b32 s9, v165
	s_ashr_i32 s8, s9, 6
	s_lshl_b32 s11, s8, 5
	v_and_b32_e32 v178, 31, v165
	s_and_b32 s11, s11, 0x60
	s_ashr_i32 s12, s9, 8
	v_or_b32_e32 v0, s11, v178
	v_lshlrev_b32_e32 v188, 10, v0
	s_lshl_b32 s30, s12, 6
	v_bfe_u32 v179, v165, 5, 1
	v_lshl_add_u64 v[0:1], s[22:23], 0, v[188:189]
	s_ashr_i32 s31, s30, 31
	v_lshl_add_u64 v[0:1], s[30:31], 1, v[0:1]
	v_lshlrev_b32_e32 v166, 4, v179
	v_lshl_add_u64 v[0:1], v[0:1], 0, v[166:167]
	global_load_dwordx4 v[158:161], v[0:1], off
	global_load_dwordx4 v[154:157], v[0:1], off offset:32
	global_load_dwordx4 v[150:153], v[0:1], off offset:64
	global_load_dwordx4 v[146:149], v[0:1], off offset:96
	s_lshl_b32 s13, s8, 3
	v_bfe_u32 v52, v165, 4, 2
	v_lshlrev_b32_e32 v182, 8, v178
	v_bitop3_b32 v1, s13, v165, v52 bitop3:0x36
	s_lshl_b32 s11, s8, 13
	v_and_b32_e32 v0, 0x1c00, v182
	v_lshlrev_b32_e32 v1, 4, v1
	v_or_b32_e32 v54, s11, v0
	v_or_b32_e32 v0, s13, v52
	v_and_b32_e32 v55, 0xf0, v1
	s_lshl_b32 s13, s8, 11
	v_lshlrev_b32_e32 v8, 4, v165
	v_lshl_or_b32 v2, v0, 10, v55
	v_or_b32_e32 v1, 4, v0
	v_bitop3_b32 v0, v0, v165, 4 bitop3:0x36
	s_add_i32 s21, s13, 0
	s_and_b32 s9, s9, 0x3fffffc0
	v_and_b32_e32 v53, 48, v8
	v_lshlrev_b32_e32 v56, 6, v179
	v_lshlrev_b32_e32 v0, 4, v0
	s_add_i32 m0, s21, 0x4000
	s_lshl_b32 s9, s9, 2
	v_or3_b32 v188, v54, v53, v56
	v_and_b32_e32 v57, 0xf0, v0
	global_load_lds_dwordx4 v2, s[40:41]
	s_mov_b32 m0, s21
	s_add_i32 s9, s9, 0
	v_lshl_or_b32 v3, v1, 10, v57
	global_load_lds_dwordx4 v188, s[48:49]
	s_add_i32 m0, s21, 0x4400
	s_add_i32 s9, s9, 0x22000
	s_or_b32 s39, s13, 0x400
	global_load_lds_dwordx4 v3, s[40:41]
	s_add_i32 m0, s21, 0x400
	s_add_u32 s30, s40, 0x10000
	v_lshl_add_u64 v[0:1], s[48:49], 0, v[188:189]
	s_addc_u32 s31, s41, 0
	v_lshl_add_u64 v[0:1], v[0:1], 0, s[34:35]
	s_add_u32 s50, s48, 0x10000
	global_load_lds_dwordx4 v[0:1], off
	s_addc_u32 s51, s49, 0
	s_add_i32 m0, s21, 0xc000
	v_or_b32_e32 v4, 0x80, v188
	global_load_lds_dwordx4 v2, s[30:31]
	s_add_i32 m0, s21, 0x8000
	v_and_b32_e32 v12, 0xf0, v8
	global_load_lds_dwordx4 v188, s[50:51]
	s_add_i32 m0, s21, 0xc400
	v_and_b32_e32 v58, 63, v165
	global_load_lds_dwordx4 v3, s[30:31]
	s_add_i32 m0, s21, 0x8400
	s_add_u32 s30, s40, 0x20000
	s_addc_u32 s31, s41, 0
	s_add_u32 s40, s48, 0x20000
	s_addc_u32 s41, s49, 0
	s_add_i32 s44, 0, 0x14000
	global_load_lds_dwordx4 v4, s[50:51]
	s_add_i32 m0, s44, s13
	s_add_i32 s48, 0, 0x10000
	global_load_lds_dwordx4 v2, s[30:31]
	s_add_i32 m0, s48, s13
	v_lshlrev_b32_e32 v14, 3, v58
	global_load_lds_dwordx4 v188, s[40:41]
	s_add_i32 m0, s44, s39
	v_or3_b32 v188, v54, v56, v53
	global_load_lds_dwordx4 v3, s[30:31]
	s_add_i32 m0, s48, s39
	s_cmp_lg_u32 0, -1
	global_load_lds_dwordx4 v4, s[40:41]
	s_cselect_b32 s13, 0, 0
	s_lshl_b32 s12, s12, 7
	v_bitop3_b32 v204, s12, v12, v166 bitop3:0x36
	v_add_u32_e32 v202, v204, v182
	v_add_u32_e32 v4, 0, v202
	s_waitcnt vmcnt(0)
	s_waitcnt vmcnt(0) lgkmcnt(0)
	s_barrier
	ds_read_b128 v[0:3], v4 offset:16384
	ds_read_b128 v[4:7], v4 offset:24576
	s_waitcnt lgkmcnt(1)
	v_mfma_f32_32x32x16_bf16 v[32:47], v[0:3], v[158:161], 0
	v_or_b32_e32 v13, s12, v166
	v_bitop3_b32 v203, v13, v12, 32 bitop3:0x36
	v_add_u32_e32 v201, v203, v182
	v_bitop3_b32 v200, v13, v12, 64 bitop3:0x36
	v_add_u32_e32 v199, v200, v182
	s_movk_i32 s12, 0x60
	v_bitop3_b32 v198, v13, v12, s12 bitop3:0x36
	s_waitcnt lgkmcnt(0)
	v_mfma_f32_32x32x16_bf16 v[16:31], v[4:7], v[158:161], 0
	v_add_u32_e32 v4, 0, v201
	ds_read_b128 v[0:3], v4 offset:16384
	ds_read_b128 v[4:7], v4 offset:24576
	v_add_u32_e32 v183, v198, v182
	s_mov_b32 s48, 0
	s_mov_b32 s49, s48
	s_mov_b32 s50, s48
	s_mov_b32 s51, s48
	s_waitcnt lgkmcnt(1)
	v_mfma_f32_32x32x16_bf16 v[32:47], v[0:3], v[154:157], v[32:47]
	v_and_b32_e32 v0, 0xc0, v8
	v_add_u32_e32 v8, 0, v199
	v_and_or_b32 v15, v14, 24, v0
	ds_read_b128 v[0:3], v8 offset:24576
	ds_read_b128 v[8:11], v8 offset:16384
	s_mov_b32 s52, s48
	s_mov_b32 s53, s48
	s_mov_b32 s54, s48
	s_waitcnt lgkmcnt(2)
	v_mfma_f32_32x32x16_bf16 v[16:31], v[4:7], v[154:157], v[16:31]
	v_lshlrev_b32_e32 v4, 1, v165
	v_and_b32_e32 v4, 32, v4
	v_and_b32_e32 v5, 0x100, v14
	v_or3_b32 v181, v15, v4, v5
	v_add_u32_e32 v4, 0, v183
	ds_read_b128 v[48:51], v4 offset:24576
	ds_read_b128 v[4:7], v4 offset:16384
	s_mov_b32 s55, s48
	s_waitcnt lgkmcnt(2)
	v_mfma_f32_32x32x16_bf16 v[32:47], v[8:11], v[150:153], v[32:47]
	s_mov_b32 s56, s48
	s_mov_b32 s57, s48
	s_mov_b32 s58, s48
	s_mov_b32 s59, s48
	s_mov_b32 s60, s48
	s_mov_b32 s61, s48
	s_mov_b32 s62, s48
	v_mfma_f32_32x32x16_bf16 v[16:31], v[0:3], v[150:153], v[16:31]
	s_mov_b32 s63, s48
	s_or_b32 s10, vcc_lo, s10
	v_cmp_gt_u32_e64 s[40:41], 32, v58
	s_mov_b32 s44, 1
	s_mov_b32 s39, 0x8000
	v_add_u32_e32 v205, s13, v181
	v_lshl_add_u32 v167, v178, 2, s9
	s_waitcnt lgkmcnt(0)
; template <bool FIRST> __device__ __forceinline__ void partialSM(f32x16& p0, f32x16& p1, float& m_reg, f32x16& negm, float& alpha) {
;   float pmax = p0[0];
; #pragma unroll
;   for (int r = 1; r < 16; ++r) pmax = fmaxf(pmax, p0[r]);
; #pragma unroll
;   for (int r = 0; r < 16; ++r) pmax = fmaxf(pmax, p1[r]);
;   { auto rr = __builtin_amdgcn_permlane32_swap(__float_as_uint(pmax), __float_as_uint(pmax), false, false);
;     pmax = fmaxf(__uint_as_float(rr[0]), __uint_as_float(rr[1])); }
;   alpha = 1.f;
;   if (FIRST || __builtin_expect(__any(pmax > THR), 0)) { const float dl = FIRST ? pmax : fmaxf(pmax, 0.f); m_reg += dl; if (!FIRST) alpha = __builtin_amdgcn_exp2f(-dl);
; #pragma unroll
;     for (int r = 0; r < 16; ++r) { p0[r] -= dl; p1[r] -= dl; }
; #pragma unroll
;     for (int r = 0; r < 16; ++r) negm[r] = -m_reg; }
; #pragma unroll
;   for (int r = 0; r < 16; ++r) p0[r] = __builtin_amdgcn_exp2f(p0[r]);
	v_mfma_f32_32x32x16_bf16 v[32:47], v[4:7], v[146:149], v[32:47]
	v_mov_b64_e32 v[0:1], s[48:49]
	v_mov_b64_e32 v[14:15], s[62:63]
	v_mov_b64_e32 v[2:3], s[50:51]
	v_mov_b64_e32 v[4:5], s[52:53]
	v_mov_b64_e32 v[6:7], s[54:55]
	v_mov_b64_e32 v[8:9], s[56:57]
	v_mov_b64_e32 v[10:11], s[58:59]
	v_mfma_f32_32x32x16_bf16 v[16:31], v[48:51], v[146:149], v[16:31]
	s_nop 3
	v_max_f32_e32 v48, v33, v33
	v_max_f32_e32 v49, v32, v32
	v_max_f32_e32 v48, v49, v48
	v_max3_f32 v48, v48, v34, v35
	v_max3_f32 v48, v48, v36, v37
	v_max3_f32 v48, v48, v38, v39
	v_max3_f32 v48, v48, v40, v41
	v_max3_f32 v48, v48, v42, v43
	v_max3_f32 v48, v48, v44, v45
	v_max3_f32 v48, v48, v46, v47
	v_max3_f32 v48, v48, v16, v17
	v_max3_f32 v48, v48, v18, v19
	v_max3_f32 v48, v48, v20, v21
	v_max3_f32 v48, v48, v22, v23
	v_max3_f32 v48, v48, v24, v25
	v_max3_f32 v48, v48, v26, v27
	v_max3_f32 v48, v48, v28, v29
	v_max3_f32 v48, v48, v30, v31
	v_mov_b32_e32 v49, v48
	s_nop 1
	v_permlane32_swap_b32_e32 v48, v49
	v_max_f32_e32 v49, v49, v49
	v_max_f32_e32 v48, v48, v48
	v_max_f32_e32 v48, v48, v49
	v_sub_f32_e32 v32, v32, v48
	v_sub_f32_e32 v33, v33, v48
	v_sub_f32_e32 v34, v34, v48
	v_sub_f32_e32 v35, v35, v48
	v_sub_f32_e32 v36, v36, v48
	v_sub_f32_e32 v37, v37, v48
	v_sub_f32_e32 v38, v38, v48
	v_sub_f32_e32 v39, v39, v48
	v_sub_f32_e32 v40, v40, v48
	v_sub_f32_e32 v41, v41, v48
	v_sub_f32_e32 v42, v42, v48
	v_sub_f32_e32 v43, v43, v48
	v_sub_f32_e32 v44, v44, v48
	v_sub_f32_e32 v45, v45, v48
	v_sub_f32_e32 v46, v46, v48
	v_sub_f32_e32 v47, v47, v48
	v_exp_f32_e32 v172, v32
	v_exp_f32_e32 v174, v33
	v_exp_f32_e32 v175, v34
	v_exp_f32_e32 v211, v35
	v_exp_f32_e32 v212, v36
	v_exp_f32_e32 v215, v37
	v_exp_f32_e32 v216, v38
	v_exp_f32_e32 v233, v39
	v_exp_f32_e32 v173, v40
	v_exp_f32_e32 v176, v41
	v_exp_f32_e32 v177, v42
	v_exp_f32_e32 v213, v43
	v_exp_f32_e32 v214, v44
	v_exp_f32_e32 v217, v45
	v_exp_f32_e32 v232, v46
	v_exp_f32_e32 v234, v47
	v_add_f32_e32 v206, 0, v48
	v_sub_f32_e32 v96, v16, v48
	v_lshl_or_b32 v16, v52, 10, s11
	v_mov_b64_e32 v[12:13], s[60:61]
	v_sub_f32_e32 v111, v31, v48
	v_sub_f32_e32 v110, v30, v48
	v_sub_f32_e32 v109, v29, v48
	v_sub_f32_e32 v108, v28, v48
	v_sub_f32_e32 v107, v27, v48
	v_sub_f32_e32 v106, v26, v48
	v_sub_f32_e32 v105, v25, v48
	v_sub_f32_e32 v104, v24, v48
	v_sub_f32_e32 v103, v23, v48
	v_sub_f32_e32 v102, v22, v48
	v_sub_f32_e32 v101, v21, v48
	v_sub_f32_e32 v100, v20, v48
	v_sub_f32_e32 v99, v19, v48
	v_sub_f32_e32 v98, v18, v48
	v_sub_f32_e32 v97, v17, v48
	v_xor_b32_e32 v80, 0x80000000, v206
	s_add_u32 s50, s42, s10
	v_or_b32_e32 v168, v16, v55
	v_or3_b32 v170, v16, v57, s18
	v_mov_b64_e32 v[62:63], v[14:15]
	v_mov_b64_e32 v[46:47], v[14:15]
	v_mov_b64_e32 v[30:31], v[14:15]
	s_addc_u32 s51, s43, vcc_hi
	v_mov_b32_e32 v169, v189
	v_mov_b32_e32 v171, v189
	v_mov_b32_e32 v180, 0
	v_mov_b32_e32 v207, 1.0
	s_mov_b32 s56, 0x18000
	v_mov_b64_e32 v[60:61], v[12:13]
	v_mov_b64_e32 v[58:59], v[10:11]
	v_mov_b64_e32 v[56:57], v[8:9]
	v_mov_b64_e32 v[54:55], v[6:7]
	v_mov_b64_e32 v[52:53], v[4:5]
	v_mov_b64_e32 v[50:51], v[2:3]
	v_mov_b64_e32 v[48:49], v[0:1]
	v_mov_b64_e32 v[44:45], v[12:13]
	v_mov_b64_e32 v[42:43], v[10:11]
	v_mov_b64_e32 v[40:41], v[8:9]
	v_mov_b64_e32 v[38:39], v[6:7]
	v_mov_b64_e32 v[36:37], v[4:5]
	v_mov_b64_e32 v[34:35], v[2:3]
	v_mov_b64_e32 v[32:33], v[0:1]
	v_mov_b64_e32 v[28:29], v[12:13]
	v_mov_b64_e32 v[26:27], v[10:11]
	v_mov_b64_e32 v[24:25], v[8:9]
	v_mov_b64_e32 v[22:23], v[6:7]
	v_mov_b64_e32 v[20:21], v[4:5]
	v_mov_b64_e32 v[18:19], v[2:3]
	v_mov_b64_e32 v[16:17], v[0:1]
	v_mov_b32_e32 v81, v80
	v_mov_b32_e32 v82, v80
	v_mov_b32_e32 v83, v80
	v_mov_b32_e32 v84, v80
	v_mov_b32_e32 v85, v80
	v_mov_b32_e32 v86, v80
	v_mov_b32_e32 v87, v80
	v_mov_b32_e32 v88, v80
	v_mov_b32_e32 v89, v80
	v_mov_b32_e32 v90, v80
	v_mov_b32_e32 v91, v80
	v_mov_b32_e32 v92, v80
	v_mov_b32_e32 v93, v80
	v_mov_b32_e32 v94, v80
	v_mov_b32_e32 v95, v80
	v_readfirstlane_b32 s98, v218
	s_nop 3
	s_lshr_b32 s98, s98, 8
	s_cmp_eq_u32 s98, 0
	s_cbranch_scc1 .Lprio_skip
	s_setprio 1
.Lprio_skip:
.LBB0_197:
	s_add_i32 s10, s39, 0
	v_add_u32_e32 v112, s10, v202
	ds_read_b128 v[236:239], v112 offset:24576
	ds_read_b128 v[112:115], v112 offset:16384
	v_add_u32_e32 v208, s10, v201
	ds_read_b128 v[68:71], v208 offset:24576
	ds_read_b128 v[72:75], v208 offset:16384
	v_add_u32_e32 v208, s10, v199
	v_exp_f32_e32 v210, v96
	v_add_f32_e32 v96, 0, v172
	v_add_f32_e32 v96, v174, v96
	s_waitcnt lgkmcnt(2)
	v_mfma_f32_32x32x16_bf16 v[128:143], v[112:115], v[158:161], v[80:95]
	v_add_f32_e32 v96, v175, v96
	v_add_f32_e32 v96, v211, v96
	v_mfma_f32_32x32x16_bf16 v[112:127], v[236:239], v[158:161], v[80:95]
	ds_read_b128 v[236:239], v208 offset:24576
	ds_read_b128 v[240:243], v208 offset:16384
	v_add_u32_e32 v208, s10, v183
	v_add_f32_e32 v96, v212, v96
	v_add_f32_e32 v96, v215, v96
	v_add_f32_e32 v96, v216, v96
	v_add_f32_e32 v96, v233, v96
	v_add_f32_e32 v96, v173, v96
	s_waitcnt lgkmcnt(2)
	v_mfma_f32_32x32x16_bf16 v[112:127], v[68:71], v[154:157], v[112:127]
	v_add_f32_e32 v96, v176, v96
	v_add_f32_e32 v96, v177, v96
	v_add_f32_e32 v96, v213, v96
	v_add_f32_e32 v96, v214, v96
	v_exp_f32_e32 v235, v97
	v_add_f32_e32 v96, v217, v96
	v_add_f32_e32 v96, v232, v96
	v_mfma_f32_32x32x16_bf16 v[128:143], v[72:75], v[154:157], v[128:143]
	ds_read_b128 v[68:71], v208 offset:24576
	ds_read_b128 v[72:75], v208 offset:16384
	v_add_f32_e32 v96, v234, v96
	v_add_f32_e32 v96, v210, v96
	v_add_f32_e32 v96, v235, v96
	v_exp_f32_e32 v244, v106
	v_exp_f32_e32 v245, v107
	s_waitcnt lgkmcnt(2)
; #define SBAR() __builtin_amdgcn_sched_barrier(0)
; __device__ __forceinline__ void finishSM(f32x16& p0, f32x16& p1, float alpha, float& l_reg, bf16x8& pa0, bf16x8& pa1, bf16x8& pa2, bf16x8& pa3) {
; #pragma unroll
;   for (int r = 0; r < 16; ++r) p1[r] = __builtin_amdgcn_exp2f(p1[r]);
;   float ps = 0;
; #pragma unroll
;   for (int r = 0; r < 16; ++r) ps += p0[r];
; #pragma unroll
;   for (int r = 0; r < 16; ++r) ps += p1[r];
;   { auto rr = __builtin_amdgcn_permlane32_swap(__float_as_uint(ps), __float_as_uint(ps), false, false);
;     ps = __uint_as_float(rr[0]) + __uint_as_float(rr[1]); }
;   l_reg = l_reg * alpha + ps;
;     ...
;   ATT_PKN(p0, 0, pa0); ATT_PKN(p0, 8, pa1); ATT_PKN(p1, 0, pa2); ATT_PKN(p1, 8, pa3);
;     ...
; }
; __device__ __forceinline__ void qkt(f32x16& p0, f32x16& p1, const bf16* Ks, const bf16x8* qr, int r32, int hi, int mp, const f32x16& negm) {
; #pragma unroll
;   for (int d0 = 0; d0 < 4; ++d0) { int cb = ((mp * 4 + d0) * 16 + hi * 8) * 2;
;     bf16x8 b0 = *reinterpret_cast<const bf16x8*>((const char*)Ks + KSWZ(r32, cb));
;     bf16x8 b1 = *reinterpret_cast<const bf16x8*>((const char*)Ks + KSWZ(32 + r32, cb));
;     if (d0 == 0) { p0 = __builtin_amdgcn_mfma_f32_32x32x16_bf16(b0, qr[0], negm, 0, 0, 0); p1 = __builtin_amdgcn_mfma_f32_32x32x16_bf16(b1, qr[0], negm, 0, 0, 0); }
;     else { p0 = __builtin_amdgcn_mfma_f32_32x32x16_bf16(b0, qr[d0], p0, 0, 0, 0); p1 = __builtin_amdgcn_mfma_f32_32x32x16_bf16(b1, qr[d0], p1, 0, 0, 0); } }
; }
; __device__ __forceinline__ int v_st(int k, int c) { const int kk = k; return ((kk >> 3) * 4 + (c >> 5)) * 512 + ((kk & 7) * 32 + (c & 31)) * 2; }
; template <int D0> __device__ __forceinline__ void pv_one(f32x16& od, int vb, bf16x8 pa0, bf16x8 pa1, bf16x8 pa2, bf16x8 pa3) {
;   const s16x4 l0 = tr_read<v_rd_off(D0, 0, 0)>(vb), h0 = tr_read<v_rd_off(D0, 0, 1)>(vb), l1 = tr_read<v_rd_off(D0, 1, 0)>(vb), h1 = tr_read<v_rd_off(D0, 1, 1)>(vb);
;   const s16x4 l2 = tr_read<v_rd_off(D0, 2, 0)>(vb), h2 = tr_read<v_rd_off(D0, 2, 1)>(vb), l3 = tr_read<v_rd_off(D0, 3, 0)>(vb), h3 = tr_read<v_rd_off(D0, 3, 1)>(vb);
;   asm volatile("s_waitcnt lgkmcnt(0)" ::: "memory"); SBAR();
;   od = __builtin_amdgcn_mfma_f32_32x32x16_bf16(pa0, ATT_PK(l0, h0), od, 0, 0, 0);
;   od = __builtin_amdgcn_mfma_f32_32x32x16_bf16(pa1, ATT_PK(l1, h1), od, 0, 0, 0);
;   od = __builtin_amdgcn_mfma_f32_32x32x16_bf16(pa2, ATT_PK(l2, h2), od, 0, 0, 0);
	v_mfma_f32_32x32x16_bf16 v[112:127], v[236:239], v[150:153], v[112:127]
	v_exp_f32_e32 v246, v108
	v_exp_f32_e32 v247, v109
	v_exp_f32_e32 v248, v110
	v_exp_f32_e32 v111, v111
	v_cvt_pk_bf16_f32 v97, v175, v211
	v_cvt_pk_bf16_f32 v109, v244, v245
	v_cvt_pk_bf16_f32 v110, v246, v247
	v_mfma_f32_32x32x16_bf16 v[128:143], v[240:243], v[150:153], v[128:143]
	s_waitcnt lgkmcnt(0)
	v_mfma_f32_32x32x16_bf16 v[112:127], v[68:71], v[146:149], v[112:127]
	v_exp_f32_e32 v236, v98
	v_exp_f32_e32 v237, v99
	v_exp_f32_e32 v238, v100
	v_exp_f32_e32 v239, v101
	v_add_f32_e32 v96, v236, v96
	v_add_f32_e32 v96, v237, v96
	v_add_f32_e32 v96, v238, v96
	v_mfma_f32_32x32x16_bf16 v[128:143], v[72:75], v[146:149], v[128:143]
	v_exp_f32_e32 v240, v102
	v_exp_f32_e32 v241, v103
	v_exp_f32_e32 v242, v104
	v_exp_f32_e32 v243, v105
	v_add_f32_e32 v96, v239, v96
	v_add_f32_e32 v96, v240, v96
	v_add_f32_e32 v96, v241, v96
	v_add_f32_e32 v96, v242, v96
	v_add_f32_e32 v96, v243, v96
	v_add_f32_e32 v96, v244, v96
	v_add_f32_e32 v96, v245, v96
	v_add_f32_e32 v96, v246, v96
	v_add_f32_e32 v96, v247, v96
	v_add_f32_e32 v96, v248, v96
	v_add_f32_e32 v208, v111, v96
	v_mov_b32_e32 v209, v208
	s_nop 1
	v_permlane32_swap_b32_e32 v208, v209
	v_cvt_pk_bf16_f32 v96, v172, v174
	v_cvt_pk_bf16_f32 v98, v212, v215
	v_cvt_pk_bf16_f32 v99, v216, v233
	v_cvt_pk_bf16_f32 v100, v173, v176
	v_cvt_pk_bf16_f32 v101, v177, v213
	v_cvt_pk_bf16_f32 v102, v214, v217
	v_cvt_pk_bf16_f32 v103, v232, v234
	v_cvt_pk_bf16_f32 v104, v210, v235
	v_cvt_pk_bf16_f32 v105, v236, v237
	v_cvt_pk_bf16_f32 v106, v238, v239
	v_cvt_pk_bf16_f32 v107, v240, v241
	v_cvt_pk_bf16_f32 v108, v242, v243
	v_cvt_pk_bf16_f32 v111, v248, v111
	v_add_u32_e32 v240, s48, v205
	ds_read_b64_tr_b16 v[210:211], v240 offset:0
	ds_read_b64_tr_b16 v[212:213], v240 offset:0x800
	ds_read_b64_tr_b16 v[214:215], v240 offset:0x1000
	ds_read_b64_tr_b16 v[216:217], v240 offset:0x1800
	ds_read_b64_tr_b16 v[232:233], v240 offset:0x2000
	ds_read_b64_tr_b16 v[234:235], v240 offset:0x2800
	ds_read_b64_tr_b16 v[236:237], v240 offset:0x3000
	ds_read_b64_tr_b16 v[238:239], v240 offset:0x3800
	s_add_i32 s12, s21, s56
	s_add_u32 s98, s50, s36
	s_addc_u32 s99, s51, s37
	s_add_u32 s100, s50, 0x4030000
	s_addc_u32 s101, s51, 0
	s_add_i32 m0, s12, 0x4000
	s_add_u32 s10, s100, 0x80
	s_addc_u32 s11, s101, 0
	global_load_lds_dwordx4 v168, s[98:99]
	s_mov_b32 m0, s12
	s_nop 0
	global_load_lds_dwordx4 v188, s[100:101]
	s_add_i32 m0, s12, 0x4400
	s_nop 0
	global_load_lds_dwordx4 v170, s[98:99]
	s_add_i32 m0, s12, 0x400
	s_nop 0
	global_load_lds_dwordx4 v188, s[10:11]
	s_waitcnt lgkmcnt(0)
	s_nop 0
	v_mfma_f32_32x32x16_bf16 v[0:15], v[96:99], v[210:213], v[0:15]
	ds_read_b64_tr_b16 v[210:211], v240 offset:0x200
	ds_read_b64_tr_b16 v[212:213], v240 offset:0xa00
	v_mfma_f32_32x32x16_bf16 v[0:15], v[100:103], v[214:217], v[0:15]
	ds_read_b64_tr_b16 v[214:215], v240 offset:0x1200
	ds_read_b64_tr_b16 v[216:217], v240 offset:0x1a00
	v_mfma_f32_32x32x16_bf16 v[0:15], v[104:107], v[232:235], v[0:15]
	ds_read_b64_tr_b16 v[232:233], v240 offset:0x2200
	ds_read_b64_tr_b16 v[234:235], v240 offset:0x2a00
	v_mfma_f32_32x32x16_bf16 v[0:15], v[108:111], v[236:239], v[0:15]
	ds_read_b64_tr_b16 v[236:237], v240 offset:0x3200
	ds_read_b64_tr_b16 v[238:239], v240 offset:0x3a00
	s_waitcnt lgkmcnt(0)
	v_mfma_f32_32x32x16_bf16 v[48:63], v[96:99], v[210:213], v[48:63]
	ds_read_b64_tr_b16 v[210:211], v240 offset:0x400
	ds_read_b64_tr_b16 v[212:213], v240 offset:0xc00
	v_mfma_f32_32x32x16_bf16 v[48:63], v[100:103], v[214:217], v[48:63]
	ds_read_b64_tr_b16 v[214:215], v240 offset:0x1400
	ds_read_b64_tr_b16 v[216:217], v240 offset:0x1c00
	v_mfma_f32_32x32x16_bf16 v[48:63], v[104:107], v[232:235], v[48:63]
	ds_read_b64_tr_b16 v[232:233], v240 offset:0x2400
	ds_read_b64_tr_b16 v[234:235], v240 offset:0x2c00
	v_mfma_f32_32x32x16_bf16 v[48:63], v[108:111], v[236:239], v[48:63]
	ds_read_b64_tr_b16 v[236:237], v240 offset:0x3400
	ds_read_b64_tr_b16 v[238:239], v240 offset:0x3c00
	s_waitcnt lgkmcnt(0)
	v_mfma_f32_32x32x16_bf16 v[32:47], v[96:99], v[210:213], v[32:47]
	ds_read_b64_tr_b16 v[210:211], v240 offset:0x600
	ds_read_b64_tr_b16 v[212:213], v240 offset:0xe00
	v_mfma_f32_32x32x16_bf16 v[32:47], v[100:103], v[214:217], v[32:47]
	ds_read_b64_tr_b16 v[214:215], v240 offset:0x1600
	ds_read_b64_tr_b16 v[216:217], v240 offset:0x1e00
	v_mfma_f32_32x32x16_bf16 v[32:47], v[104:107], v[232:235], v[32:47]
	ds_read_b64_tr_b16 v[232:233], v240 offset:0x2600
	ds_read_b64_tr_b16 v[234:235], v240 offset:0x2e00
	v_mfma_f32_32x32x16_bf16 v[32:47], v[108:111], v[236:239], v[32:47]
	ds_read_b64_tr_b16 v[236:237], v240 offset:0x3600
	ds_read_b64_tr_b16 v[238:239], v240 offset:0x3e00
	s_waitcnt lgkmcnt(0)
	v_mfma_f32_32x32x16_bf16 v[16:31], v[96:99], v[210:213], v[16:31]
	v_max_f32_e32 v96, v129, v129
	v_max_f32_e32 v97, v128, v128
	v_max_f32_e32 v96, v97, v96
	v_max3_f32 v96, v96, v130, v131
	v_max3_f32 v96, v96, v132, v133
	v_max3_f32 v96, v96, v134, v135
	v_max3_f32 v96, v96, v136, v137
	v_mfma_f32_32x32x16_bf16 v[16:31], v[100:103], v[214:217], v[16:31]
	v_max3_f32 v96, v96, v138, v139
	v_max3_f32 v96, v96, v140, v141
	v_max3_f32 v96, v96, v142, v143
	v_max3_f32 v96, v96, v112, v113
	v_max3_f32 v96, v96, v114, v115
	v_max3_f32 v96, v96, v116, v117
	v_max3_f32 v96, v96, v118, v119
	v_mfma_f32_32x32x16_bf16 v[16:31], v[104:107], v[232:235], v[16:31]
	v_max3_f32 v96, v96, v120, v121
	v_max3_f32 v96, v96, v122, v123
	v_max3_f32 v96, v96, v124, v125
	v_max3_f32 v96, v96, v126, v127
	v_mov_b32_e32 v97, v96
	s_nop 1
	v_permlane32_swap_b32_e32 v96, v97
	v_mfma_f32_32x32x16_bf16 v[16:31], v[108:111], v[236:239], v[16:31]
	v_max_f32_e32 v97, v97, v97
	v_max_f32_e32 v96, v96, v96
	v_max_f32_e32 v96, v96, v97
	v_cmp_lt_f32_e32 vcc, s19, v96
	s_cbranch_vccnz .LBB0_215
	v_mov_b32_e32 v210, 1.0
	v_cmp_gt_f32_e32 vcc, 1.0, v210
	s_cbranch_vccz .LBB0_202

; #define ATT_PKN(P, BASE, OUT) do { u32x4 w = {cvtpk(P[BASE + 0], P[BASE + 1]), cvtpk(P[BASE + 2], P[BASE + 3]), cvtpk(P[BASE + 4], P[BASE + 5]), cvtpk(P[BASE + 6], P[BASE + 7])}; OUT = *reinterpret_cast<bf16x8*>(&w); } while (0)
; __device__ __forceinline__ void finishSM(f32x16& p0, f32x16& p1, float alpha, float& l_reg, bf16x8& pa0, bf16x8& pa1, bf16x8& pa2, bf16x8& pa3) {
; #pragma unroll
;   for (int r = 0; r < 16; ++r) p1[r] = __builtin_amdgcn_exp2f(p1[r]);
;   float ps = 0;
; #pragma unroll
;   for (int r = 0; r < 16; ++r) ps += p0[r];
; #pragma unroll
;   for (int r = 0; r < 16; ++r) ps += p1[r];
;   { auto rr = __builtin_amdgcn_permlane32_swap(__float_as_uint(ps), __float_as_uint(ps), false, false);
;     ps = __uint_as_float(rr[0]) + __uint_as_float(rr[1]); }
;   l_reg = l_reg * alpha + ps;
;     ...
;   ATT_PKN(p0, 0, pa0); ATT_PKN(p0, 8, pa1); ATT_PKN(p1, 0, pa2); ATT_PKN(p1, 8, pa3);
;     ...
; }
; __device__ __forceinline__ void qkt(f32x16& p0, f32x16& p1, const bf16* Ks, const bf16x8* qr, int r32, int hi, int mp, const f32x16& negm) {
; #pragma unroll
;   for (int d0 = 0; d0 < 4; ++d0) { int cb = ((mp * 4 + d0) * 16 + hi * 8) * 2;
;     bf16x8 b0 = *reinterpret_cast<const bf16x8*>((const char*)Ks + KSWZ(r32, cb));
;     bf16x8 b1 = *reinterpret_cast<const bf16x8*>((const char*)Ks + KSWZ(32 + r32, cb));
;     if (d0 == 0) { p0 = __builtin_amdgcn_mfma_f32_32x32x16_bf16(b0, qr[0], negm, 0, 0, 0); p1 = __builtin_amdgcn_mfma_f32_32x32x16_bf16(b1, qr[0], negm, 0, 0, 0); }
;     else { p0 = __builtin_amdgcn_mfma_f32_32x32x16_bf16(b0, qr[d0], p0, 0, 0, 0); p1 = __builtin_amdgcn_mfma_f32_32x32x16_bf16(b1, qr[d0], p1, 0, 0, 0); } }
; }
.LBB0_217:
	s_setprio 0
	v_mov_b64_e32 v[64:65], v[80:81]
	v_mov_b64_e32 v[66:67], v[82:83]
	v_mov_b64_e32 v[68:69], v[84:85]
	v_mov_b64_e32 v[70:71], v[86:87]
	v_mov_b64_e32 v[72:73], v[88:89]
	v_mov_b64_e32 v[74:75], v[90:91]
	v_mov_b64_e32 v[76:77], v[92:93]
	v_mov_b64_e32 v[78:79], v[94:95]
	v_or_b32_e32 v113, 0x2000, v182
	s_add_i32 s10, 0, 0x1c000
	v_add3_u32 v80, v204, v113, s10
	ds_read_b128 v[114:117], v80
	v_add_u32_e32 v80, s10, v202
	ds_read_b128 v[118:121], v80
	v_exp_f32_e32 v122, v105
	v_exp_f32_e32 v123, v106
	v_exp_f32_e32 v124, v107
	v_exp_f32_e32 v125, v108
	v_exp_f32_e32 v126, v109
	v_exp_f32_e32 v110, v110
	v_exp_f32_e32 v111, v111
	s_waitcnt lgkmcnt(0)
	v_mfma_f32_32x32x16_bf16 v[80:95], v[118:121], v[158:161], v[64:79]
	v_add_u32_e32 v118, s10, v201
	ds_read_b128 v[118:121], v118
	v_cvt_pk_bf16_f32 v105, v232, v234
	v_mfma_f32_32x32x16_bf16 v[64:79], v[114:117], v[158:161], v[64:79]
	v_add3_u32 v114, v203, v113, s10
	ds_read_b128 v[114:117], v114
	s_waitcnt lgkmcnt(0)
	v_mfma_f32_32x32x16_bf16 v[64:79], v[114:117], v[154:157], v[64:79]
	v_add3_u32 v114, v200, v113, s10
	ds_read_b128 v[114:117], v114
	v_add3_u32 v113, v198, v113, s10
	s_waitcnt lgkmcnt(0)
	v_mfma_f32_32x32x16_bf16 v[64:79], v[114:117], v[150:153], v[64:79]
	ds_read_b128 v[114:117], v113
	v_add_u32_e32 v113, s10, v183
	v_mfma_f32_32x32x16_bf16 v[80:95], v[118:121], v[154:157], v[80:95]
	v_add_u32_e32 v118, s10, v199
	ds_read_b128 v[118:121], v118
	s_waitcnt lgkmcnt(0)
	v_mfma_f32_32x32x16_bf16 v[80:95], v[118:121], v[150:153], v[80:95]
	ds_read_b128 v[118:121], v113
	v_exp_f32_e32 v113, v96
	v_add_f32_e32 v96, 0, v172
	v_add_f32_e32 v96, v174, v96
	v_add_f32_e32 v96, v175, v96
	v_add_f32_e32 v96, v211, v96
	v_add_f32_e32 v96, v212, v96
	v_add_f32_e32 v96, v215, v96
	v_add_f32_e32 v96, v216, v96
	v_add_f32_e32 v96, v233, v96
	v_add_f32_e32 v96, v173, v96
	v_add_f32_e32 v96, v176, v96
	v_add_f32_e32 v96, v177, v96
	v_add_f32_e32 v96, v213, v96
	v_add_f32_e32 v96, v214, v96
	v_mfma_f32_32x32x16_bf16 v[64:79], v[114:117], v[146:149], v[64:79]
	v_exp_f32_e32 v114, v97
	v_add_f32_e32 v96, v217, v96
	v_exp_f32_e32 v115, v98
	v_add_f32_e32 v96, v232, v96
	v_exp_f32_e32 v116, v99
	v_add_f32_e32 v96, v234, v96
	v_exp_f32_e32 v117, v100
	v_add_f32_e32 v96, v113, v96
	s_waitcnt lgkmcnt(0)
	v_mfma_f32_32x32x16_bf16 v[80:95], v[118:121], v[146:149], v[80:95]
	v_exp_f32_e32 v118, v101
	v_add_f32_e32 v96, v114, v96
	v_exp_f32_e32 v119, v102
	v_add_f32_e32 v96, v115, v96
	v_exp_f32_e32 v120, v103
	v_add_f32_e32 v96, v116, v96
	v_exp_f32_e32 v121, v104
	v_add_f32_e32 v96, v117, v96
	v_add_f32_e32 v96, v118, v96
	v_add_f32_e32 v96, v119, v96
	v_add_f32_e32 v96, v120, v96
	v_add_f32_e32 v96, v121, v96
	v_add_f32_e32 v96, v122, v96
	v_add_f32_e32 v96, v123, v96
	v_add_f32_e32 v96, v124, v96
	v_add_f32_e32 v96, v125, v96
	v_add_f32_e32 v96, v126, v96
	v_add_f32_e32 v96, v110, v96
	v_add_f32_e32 v96, v111, v96
	v_mov_b32_e32 v97, v96
	s_nop 1
	v_permlane32_swap_b32_e32 v96, v97
	v_cvt_pk_bf16_f32 v98, v172, v174
	v_cvt_pk_bf16_f32 v99, v175, v211
	v_cvt_pk_bf16_f32 v100, v212, v215
	v_cvt_pk_bf16_f32 v101, v216, v233
	v_cvt_pk_bf16_f32 v102, v173, v176
	v_cvt_pk_bf16_f32 v103, v177, v213
	v_cvt_pk_bf16_f32 v104, v214, v217
	v_cvt_pk_bf16_f32 v106, v113, v114
	v_cvt_pk_bf16_f32 v107, v115, v116
	v_cvt_pk_bf16_f32 v108, v117, v118
	v_cvt_pk_bf16_f32 v109, v119, v120
	v_cvt_pk_bf16_f32 v114, v121, v122
	v_cvt_pk_bf16_f32 v115, v123, v124
	v_cvt_pk_bf16_f32 v116, v125, v126
	v_cvt_pk_bf16_f32 v117, v110, v111
	s_cmp_lg_u32 0, -1
	s_cselect_b32 s10, 0, 0
	s_add_i32 s10, s10, 0x10000
	v_add_u32_e32 v110, s10, v181
	ds_read_b64_tr_b16 v[118:119], v110 offset:0
	ds_read_b64_tr_b16 v[120:121], v110 offset:0x800
	ds_read_b64_tr_b16 v[122:123], v110 offset:0x1000
	ds_read_b64_tr_b16 v[124:125], v110 offset:0x1800
	ds_read_b64_tr_b16 v[126:127], v110 offset:0x2000
	ds_read_b64_tr_b16 v[128:129], v110 offset:0x2800
	ds_read_b64_tr_b16 v[130:131], v110 offset:0x3000
	ds_read_b64_tr_b16 v[132:133], v110 offset:0x3800
	s_waitcnt lgkmcnt(0)
; #define SBAR() __builtin_amdgcn_sched_barrier(0)
; template <int OFF> __device__ __forceinline__ s16x4 tr_read(int vb) { s16x4 r; asm volatile("ds_read_b64_tr_b16 %0, %1 offset:%2" : "=&v"(r) : "v"(vb), "i"(OFF) : "memory"); return r; }
; template <bool FIRST> __device__ __forceinline__ void partialSM(f32x16& p0, f32x16& p1, float& m_reg, f32x16& negm, float& alpha) {
;   float pmax = p0[0];
; #pragma unroll
;   for (int r = 1; r < 16; ++r) pmax = fmaxf(pmax, p0[r]);
; #pragma unroll
;   for (int r = 0; r < 16; ++r) pmax = fmaxf(pmax, p1[r]);
;   { auto rr = __builtin_amdgcn_permlane32_swap(__float_as_uint(pmax), __float_as_uint(pmax), false, false);
;     pmax = fmaxf(__uint_as_float(rr[0]), __uint_as_float(rr[1])); }
;   alpha = 1.f;
;   if (FIRST || __builtin_expect(__any(pmax > THR), 0)) { const float dl = FIRST ? pmax : fmaxf(pmax, 0.f); m_reg += dl; if (!FIRST) alpha = __builtin_amdgcn_exp2f(-dl);
; template <int D0> __device__ __forceinline__ void pv_one(f32x16& od, int vb, bf16x8 pa0, bf16x8 pa1, bf16x8 pa2, bf16x8 pa3) {
;   const s16x4 l0 = tr_read<v_rd_off(D0, 0, 0)>(vb), h0 = tr_read<v_rd_off(D0, 0, 1)>(vb), l1 = tr_read<v_rd_off(D0, 1, 0)>(vb), h1 = tr_read<v_rd_off(D0, 1, 1)>(vb);
;   const s16x4 l2 = tr_read<v_rd_off(D0, 2, 0)>(vb), h2 = tr_read<v_rd_off(D0, 2, 1)>(vb), l3 = tr_read<v_rd_off(D0, 3, 0)>(vb), h3 = tr_read<v_rd_off(D0, 3, 1)>(vb);
;   asm volatile("s_waitcnt lgkmcnt(0)" ::: "memory"); SBAR();
;   od = __builtin_amdgcn_mfma_f32_32x32x16_bf16(pa0, ATT_PK(l0, h0), od, 0, 0, 0);
;   od = __builtin_amdgcn_mfma_f32_32x32x16_bf16(pa1, ATT_PK(l1, h1), od, 0, 0, 0);
;   od = __builtin_amdgcn_mfma_f32_32x32x16_bf16(pa2, ATT_PK(l2, h2), od, 0, 0, 0);
;   od = __builtin_amdgcn_mfma_f32_32x32x16_bf16(pa3, ATT_PK(l3, h3), od, 0, 0, 0);
; }
; __device__ __forceinline__ void pv_d0(f32x16* o, int vb, bf16x8 pa0, bf16x8 pa1, bf16x8 pa2, bf16x8 pa3) {
;   pv_one<0>(o[0], vb, pa0, pa1, pa2, pa3); pv_one<1>(o[1], vb, pa0, pa1, pa2, pa3); pv_one<2>(o[2], vb, pa0, pa1, pa2, pa3); pv_one<3>(o[3], vb, pa0, pa1, pa2, pa3);
	s_nop 0
	v_mfma_f32_32x32x16_bf16 v[0:15], v[98:101], v[118:121], v[0:15]
	ds_read_b64_tr_b16 v[118:119], v110 offset:0x200
	ds_read_b64_tr_b16 v[120:121], v110 offset:0xa00
	v_mfma_f32_32x32x16_bf16 v[0:15], v[102:105], v[122:125], v[0:15]
	ds_read_b64_tr_b16 v[122:123], v110 offset:0x1200
	ds_read_b64_tr_b16 v[124:125], v110 offset:0x1a00
	v_mfma_f32_32x32x16_bf16 v[0:15], v[106:109], v[126:129], v[0:15]
	ds_read_b64_tr_b16 v[126:127], v110 offset:0x2200
	ds_read_b64_tr_b16 v[128:129], v110 offset:0x2a00
	v_mfma_f32_32x32x16_bf16 v[0:15], v[114:117], v[130:133], v[0:15]
	ds_read_b64_tr_b16 v[130:131], v110 offset:0x3200
	ds_read_b64_tr_b16 v[132:133], v110 offset:0x3a00
	s_waitcnt lgkmcnt(0)
	v_mfma_f32_32x32x16_bf16 v[48:63], v[98:101], v[118:121], v[48:63]
	ds_read_b64_tr_b16 v[118:119], v110 offset:0x400
	ds_read_b64_tr_b16 v[120:121], v110 offset:0xc00
	v_mfma_f32_32x32x16_bf16 v[48:63], v[102:105], v[122:125], v[48:63]
	ds_read_b64_tr_b16 v[122:123], v110 offset:0x1400
	ds_read_b64_tr_b16 v[124:125], v110 offset:0x1c00
	v_mfma_f32_32x32x16_bf16 v[48:63], v[106:109], v[126:129], v[48:63]
	ds_read_b64_tr_b16 v[126:127], v110 offset:0x2400
	ds_read_b64_tr_b16 v[128:129], v110 offset:0x2c00
	v_mfma_f32_32x32x16_bf16 v[48:63], v[114:117], v[130:133], v[48:63]
	ds_read_b64_tr_b16 v[130:131], v110 offset:0x3400
	ds_read_b64_tr_b16 v[132:133], v110 offset:0x3c00
	s_waitcnt lgkmcnt(0)
	v_mfma_f32_32x32x16_bf16 v[32:47], v[98:101], v[118:121], v[32:47]
	ds_read_b64_tr_b16 v[118:119], v110 offset:0x600
	ds_read_b64_tr_b16 v[120:121], v110 offset:0xe00
	v_mfma_f32_32x32x16_bf16 v[32:47], v[102:105], v[122:125], v[32:47]
	ds_read_b64_tr_b16 v[122:123], v110 offset:0x1600
	ds_read_b64_tr_b16 v[124:125], v110 offset:0x1e00
	v_mfma_f32_32x32x16_bf16 v[32:47], v[106:109], v[126:129], v[32:47]
	ds_read_b64_tr_b16 v[126:127], v110 offset:0x2600
	ds_read_b64_tr_b16 v[128:129], v110 offset:0x2e00
	v_mfma_f32_32x32x16_bf16 v[32:47], v[114:117], v[130:133], v[32:47]
	ds_read_b64_tr_b16 v[130:131], v110 offset:0x3600
	ds_read_b64_tr_b16 v[132:133], v110 offset:0x3e00
	s_waitcnt lgkmcnt(0)
	v_mfma_f32_32x32x16_bf16 v[16:31], v[98:101], v[118:121], v[16:31]
	v_max_f32_e32 v98, v81, v81
	v_max_f32_e32 v99, v80, v80
	v_max_f32_e32 v98, v99, v98
	v_max3_f32 v98, v98, v82, v83
	v_max3_f32 v98, v98, v84, v85
	v_max3_f32 v98, v98, v86, v87
	v_max3_f32 v98, v98, v88, v89
	v_mfma_f32_32x32x16_bf16 v[16:31], v[102:105], v[122:125], v[16:31]
	v_max3_f32 v98, v98, v90, v91
	v_max3_f32 v98, v98, v92, v93
	v_max3_f32 v98, v98, v94, v95
	v_max3_f32 v98, v98, v64, v65
	v_max3_f32 v98, v98, v66, v67
	v_max3_f32 v98, v98, v68, v69
	v_max3_f32 v98, v98, v70, v71
	v_mfma_f32_32x32x16_bf16 v[16:31], v[106:109], v[126:129], v[16:31]
	v_max3_f32 v98, v98, v72, v73
	v_max3_f32 v98, v98, v74, v75
	v_max3_f32 v98, v98, v76, v77
	v_max3_f32 v98, v98, v78, v79
	v_mov_b32_e32 v99, v98
	s_nop 1
	v_permlane32_swap_b32_e32 v98, v99
	v_mfma_f32_32x32x16_bf16 v[16:31], v[114:117], v[130:133], v[16:31]
	v_max_f32_e32 v99, v99, v99
	v_max_f32_e32 v98, v98, v98
	v_max_f32_e32 v99, v98, v99
	v_cmp_lt_f32_e32 vcc, s19, v99
	v_mov_b32_e32 v98, 1.0
	s_cbranch_vccnz .LBB0_224
	v_cmp_gt_f32_e32 vcc, 1.0, v98
	s_cbranch_vccz .LBB0_222
